# P4a: prefetch next unit's gate tile (one dword per 128B line) at the end of the current unit epilogue
# baseline (speedup 1.0000x reference)
.LBB0_747:
	v_lshl_add_u32 v150, s64, 8, v165
	v_lshl_or_b32 v148, s88, 8, v167
	v_ashrrev_i32_e32 v151, 31, v150
	v_ashrrev_i32_e32 v149, 31, v148
	v_lshlrev_b64 v[146:147], 10, v[150:151]
	v_lshl_add_u64 v[146:147], v[146:147], 0, v[148:149]
	v_lshlrev_b64 v[146:147], 1, v[146:147]
	v_lshl_add_u64 v[172:173], s[14:15], 0, v[146:147]
	global_load_dwordx4 v[172:175], v[172:173], off
	v_or_b32_e32 v176, 0x100, v146
	v_mov_b32_e32 v177, v147
	v_lshl_add_u64 v[178:179], s[14:15], 0, v[176:177]
	v_lshl_add_u64 v[176:177], s[6:7], 0, v[176:177]
	s_andn2_b64 vcc, exec, s[0:1]
	s_mov_b64 s[0:1], -1
	s_waitcnt vmcnt(0)
	v_lshlrev_b32_e32 v180, 16, v172
	v_and_b32_e32 v181, 0xffff0000, v172
	v_lshlrev_b32_e32 v172, 16, v173
	v_and_b32_e32 v173, 0xffff0000, v173
	v_lshlrev_b32_e32 v182, 16, v174
	v_and_b32_e32 v183, 0xffff0000, v174
	v_lshlrev_b32_e32 v174, 16, v175
	v_and_b32_e32 v175, 0xffff0000, v175
	v_pk_mul_f32 v[128:129], v[128:129], v[172:173]
	v_pk_mul_f32 v[126:127], v[126:127], v[180:181]
	v_pk_mul_f32 v[172:173], v[124:125], v[174:175]
	v_pk_mul_f32 v[124:125], v[122:123], v[182:183]
	v_cvt_pk_bf16_f32 v122, v126, v127
	v_cvt_pk_bf16_f32 v123, v128, v129
	v_lshl_add_u64 v[174:175], s[6:7], 0, v[146:147]
	v_cvt_pk_bf16_f32 v124, v124, v125
	v_cvt_pk_bf16_f32 v125, v172, v173
	global_load_dwordx4 v[126:129], v[178:179], off
	v_or_b32_e32 v172, 16, v150
	v_ashrrev_i32_e32 v173, 31, v172
	v_lshlrev_b64 v[172:173], 10, v[172:173]
	v_lshl_add_u64 v[172:173], v[172:173], 0, v[148:149]
	global_store_dwordx4 v[174:175], v[122:125], off
	v_lshlrev_b64 v[172:173], 1, v[172:173]
	v_lshl_add_u64 v[178:179], s[14:15], 0, v[172:173]
	s_waitcnt vmcnt(1)
	v_lshlrev_b32_e32 v122, 16, v126
	v_and_b32_e32 v123, 0xffff0000, v126
	v_lshlrev_b32_e32 v124, 16, v127
	v_and_b32_e32 v125, 0xffff0000, v127
	v_lshlrev_b32_e32 v126, 16, v128
	v_and_b32_e32 v127, 0xffff0000, v128
	v_lshlrev_b32_e32 v128, 16, v129
	v_and_b32_e32 v129, 0xffff0000, v129
	v_pk_mul_f32 v[118:119], v[118:119], v[122:123]
	v_pk_mul_f32 v[122:123], v[116:117], v[128:129]
	v_pk_mul_f32 v[116:117], v[114:115], v[126:127]
	v_pk_mul_f32 v[120:121], v[120:121], v[124:125]
	v_cvt_pk_bf16_f32 v114, v118, v119
	v_lshl_add_u64 v[118:119], s[6:7], 0, v[172:173]
	v_cvt_pk_bf16_f32 v115, v120, v121
	v_cvt_pk_bf16_f32 v116, v116, v117
	v_cvt_pk_bf16_f32 v117, v122, v123
	global_store_dwordx4 v[176:177], v[114:117], off
	global_load_dwordx4 v[114:117], v[178:179], off
	v_or_b32_e32 v172, 0x100, v172
	v_lshl_add_u64 v[120:121], s[14:15], 0, v[172:173]
	s_waitcnt vmcnt(0)
	v_lshlrev_b32_e32 v122, 16, v114
	v_and_b32_e32 v123, 0xffff0000, v114
	v_lshlrev_b32_e32 v114, 16, v115
	v_and_b32_e32 v115, 0xffff0000, v115
	v_lshlrev_b32_e32 v124, 16, v116
	v_and_b32_e32 v125, 0xffff0000, v116
	v_lshlrev_b32_e32 v116, 16, v117
	v_and_b32_e32 v117, 0xffff0000, v117
	v_pk_mul_f32 v[112:113], v[112:113], v[114:115]
	v_pk_mul_f32 v[110:111], v[110:111], v[122:123]
	v_pk_mul_f32 v[114:115], v[108:109], v[116:117]
	v_pk_mul_f32 v[108:109], v[106:107], v[124:125]
	v_cvt_pk_bf16_f32 v106, v110, v111
	v_cvt_pk_bf16_f32 v107, v112, v113
	s_nop 0
	v_cvt_pk_bf16_f32 v108, v108, v109
	v_cvt_pk_bf16_f32 v109, v114, v115
	global_load_dwordx4 v[110:113], v[120:121], off
	v_or_b32_e32 v114, 32, v150
	v_ashrrev_i32_e32 v115, 31, v114
	v_lshlrev_b64 v[114:115], 10, v[114:115]
	v_lshl_add_u64 v[114:115], v[114:115], 0, v[148:149]
	global_store_dwordx4 v[118:119], v[106:109], off
	v_lshlrev_b64 v[114:115], 1, v[114:115]
	v_lshl_add_u64 v[120:121], s[6:7], 0, v[172:173]
	v_lshl_add_u64 v[116:117], s[14:15], 0, v[114:115]
	s_waitcnt vmcnt(1)
	v_lshlrev_b32_e32 v106, 16, v110
	v_and_b32_e32 v107, 0xffff0000, v110
	v_lshlrev_b32_e32 v108, 16, v111
	v_and_b32_e32 v109, 0xffff0000, v111
	v_lshlrev_b32_e32 v110, 16, v112
	v_and_b32_e32 v111, 0xffff0000, v112
	v_lshlrev_b32_e32 v112, 16, v113
	v_and_b32_e32 v113, 0xffff0000, v113
	v_pk_mul_f32 v[102:103], v[102:103], v[106:107]
	v_pk_mul_f32 v[106:107], v[100:101], v[112:113]
	v_pk_mul_f32 v[100:101], v[98:99], v[110:111]
	v_pk_mul_f32 v[104:105], v[104:105], v[108:109]
	v_cvt_pk_bf16_f32 v98, v102, v103
	v_lshl_add_u64 v[102:103], s[6:7], 0, v[114:115]
	v_cvt_pk_bf16_f32 v99, v104, v105
	v_cvt_pk_bf16_f32 v100, v100, v101
	v_cvt_pk_bf16_f32 v101, v106, v107
	global_store_dwordx4 v[120:121], v[98:101], off
	global_load_dwordx4 v[98:101], v[116:117], off
	v_or_b32_e32 v114, 0x100, v114
	v_lshl_add_u64 v[104:105], s[14:15], 0, v[114:115]
	s_waitcnt vmcnt(0)
	v_lshlrev_b32_e32 v106, 16, v98
	v_and_b32_e32 v107, 0xffff0000, v98
	v_lshlrev_b32_e32 v98, 16, v99
	v_and_b32_e32 v99, 0xffff0000, v99
	v_lshlrev_b32_e32 v108, 16, v100
	v_and_b32_e32 v109, 0xffff0000, v100
	v_lshlrev_b32_e32 v100, 16, v101
	v_and_b32_e32 v101, 0xffff0000, v101
	v_pk_mul_f32 v[96:97], v[96:97], v[98:99]
	v_pk_mul_f32 v[94:95], v[94:95], v[106:107]
	v_pk_mul_f32 v[98:99], v[92:93], v[100:101]
	v_pk_mul_f32 v[92:93], v[90:91], v[108:109]
	v_cvt_pk_bf16_f32 v90, v94, v95
	v_cvt_pk_bf16_f32 v91, v96, v97
	s_nop 0
	v_cvt_pk_bf16_f32 v92, v92, v93
	v_cvt_pk_bf16_f32 v93, v98, v99
	global_load_dwordx4 v[94:97], v[104:105], off
	v_or_b32_e32 v98, 48, v150
	v_ashrrev_i32_e32 v99, 31, v98
	v_lshlrev_b64 v[98:99], 10, v[98:99]
	v_lshl_add_u64 v[98:99], v[98:99], 0, v[148:149]
	global_store_dwordx4 v[102:103], v[90:93], off
	v_lshlrev_b64 v[98:99], 1, v[98:99]
	v_lshl_add_u64 v[104:105], s[6:7], 0, v[114:115]
	v_lshl_add_u64 v[100:101], s[14:15], 0, v[98:99]
	s_waitcnt vmcnt(1)
	v_lshlrev_b32_e32 v90, 16, v94
	v_and_b32_e32 v91, 0xffff0000, v94
	v_lshlrev_b32_e32 v92, 16, v95
	v_and_b32_e32 v93, 0xffff0000, v95
	v_lshlrev_b32_e32 v94, 16, v96
	v_and_b32_e32 v95, 0xffff0000, v96
	v_lshlrev_b32_e32 v96, 16, v97
	v_and_b32_e32 v97, 0xffff0000, v97
	v_pk_mul_f32 v[86:87], v[86:87], v[90:91]
	v_pk_mul_f32 v[90:91], v[84:85], v[96:97]
	v_pk_mul_f32 v[84:85], v[82:83], v[94:95]
	v_pk_mul_f32 v[88:89], v[88:89], v[92:93]
	v_cvt_pk_bf16_f32 v82, v86, v87
	v_lshl_add_u64 v[86:87], s[6:7], 0, v[98:99]
	v_cvt_pk_bf16_f32 v83, v88, v89
	v_cvt_pk_bf16_f32 v84, v84, v85
	v_cvt_pk_bf16_f32 v85, v90, v91
	global_store_dwordx4 v[104:105], v[82:85], off
	global_load_dwordx4 v[82:85], v[100:101], off
	v_or_b32_e32 v98, 0x100, v98
	v_lshl_add_u64 v[88:89], s[14:15], 0, v[98:99]
	s_waitcnt vmcnt(0)
	v_lshlrev_b32_e32 v90, 16, v82
	v_and_b32_e32 v91, 0xffff0000, v82
	v_lshlrev_b32_e32 v82, 16, v83
	v_and_b32_e32 v83, 0xffff0000, v83
	v_lshlrev_b32_e32 v92, 16, v84
	v_and_b32_e32 v93, 0xffff0000, v84
	v_lshlrev_b32_e32 v84, 16, v85
	v_and_b32_e32 v85, 0xffff0000, v85
	v_pk_mul_f32 v[80:81], v[80:81], v[82:83]
	v_pk_mul_f32 v[78:79], v[78:79], v[90:91]
	v_pk_mul_f32 v[82:83], v[76:77], v[84:85]
	v_pk_mul_f32 v[76:77], v[74:75], v[92:93]
	v_cvt_pk_bf16_f32 v74, v78, v79
	v_cvt_pk_bf16_f32 v75, v80, v81
	s_nop 0
	v_cvt_pk_bf16_f32 v76, v76, v77
	v_cvt_pk_bf16_f32 v77, v82, v83
	global_load_dwordx4 v[78:81], v[88:89], off
	v_lshl_add_u64 v[82:83], v[146:147], 0, s[10:11]
	global_store_dwordx4 v[86:87], v[74:77], off
	v_lshl_add_u64 v[88:89], s[6:7], 0, v[98:99]
	v_lshl_add_u64 v[84:85], s[14:15], 0, v[82:83]
	s_waitcnt vmcnt(1)
	v_lshlrev_b32_e32 v74, 16, v78
	v_and_b32_e32 v75, 0xffff0000, v78
	v_lshlrev_b32_e32 v76, 16, v79
	v_and_b32_e32 v77, 0xffff0000, v79
	v_lshlrev_b32_e32 v78, 16, v80
	v_and_b32_e32 v79, 0xffff0000, v80
	v_lshlrev_b32_e32 v80, 16, v81
	v_and_b32_e32 v81, 0xffff0000, v81
	v_pk_mul_f32 v[70:71], v[70:71], v[74:75]
	v_pk_mul_f32 v[74:75], v[68:69], v[80:81]
	v_pk_mul_f32 v[68:69], v[66:67], v[78:79]
	v_pk_mul_f32 v[72:73], v[72:73], v[76:77]
	v_cvt_pk_bf16_f32 v66, v70, v71
	v_lshl_add_u64 v[70:71], v[146:147], 0, s[20:21]
	v_cvt_pk_bf16_f32 v67, v72, v73
	v_cvt_pk_bf16_f32 v68, v68, v69
	v_cvt_pk_bf16_f32 v69, v74, v75
	global_store_dwordx4 v[88:89], v[66:69], off
	global_load_dwordx4 v[66:69], v[84:85], off
	v_lshl_add_u64 v[72:73], s[14:15], 0, v[70:71]
	v_lshl_add_u64 v[70:71], s[6:7], 0, v[70:71]
	s_waitcnt vmcnt(0)
	v_lshlrev_b32_e32 v74, 16, v66
	v_and_b32_e32 v75, 0xffff0000, v66
	v_lshlrev_b32_e32 v66, 16, v67
	v_and_b32_e32 v67, 0xffff0000, v67
	v_lshlrev_b32_e32 v76, 16, v68
	v_and_b32_e32 v77, 0xffff0000, v68
	v_lshlrev_b32_e32 v68, 16, v69
	v_and_b32_e32 v69, 0xffff0000, v69
	v_pk_mul_f32 v[64:65], v[64:65], v[66:67]
	v_pk_mul_f32 v[62:63], v[62:63], v[74:75]
	v_pk_mul_f32 v[66:67], v[60:61], v[68:69]
	v_pk_mul_f32 v[60:61], v[58:59], v[76:77]
	v_cvt_pk_bf16_f32 v58, v62, v63
	v_cvt_pk_bf16_f32 v59, v64, v65
	v_lshl_add_u64 v[68:69], s[6:7], 0, v[82:83]
	v_cvt_pk_bf16_f32 v60, v60, v61
	v_cvt_pk_bf16_f32 v61, v66, v67
	global_load_dwordx4 v[62:65], v[72:73], off
	v_lshl_add_u64 v[66:67], v[146:147], 0, s[22:23]
	global_store_dwordx4 v[68:69], v[58:61], off
	v_lshl_add_u64 v[72:73], s[14:15], 0, v[66:67]
	s_waitcnt vmcnt(1)
	v_lshlrev_b32_e32 v58, 16, v62
	v_and_b32_e32 v59, 0xffff0000, v62
	v_lshlrev_b32_e32 v60, 16, v63
	v_and_b32_e32 v61, 0xffff0000, v63
	v_lshlrev_b32_e32 v62, 16, v64
	v_and_b32_e32 v63, 0xffff0000, v64
	v_lshlrev_b32_e32 v64, 16, v65
	v_and_b32_e32 v65, 0xffff0000, v65
	v_pk_mul_f32 v[54:55], v[54:55], v[58:59]
	v_pk_mul_f32 v[58:59], v[52:53], v[64:65]
	v_pk_mul_f32 v[52:53], v[50:51], v[62:63]
	v_pk_mul_f32 v[56:57], v[56:57], v[60:61]
	v_cvt_pk_bf16_f32 v50, v54, v55
	v_lshl_add_u64 v[54:55], v[146:147], 0, s[24:25]
	v_cvt_pk_bf16_f32 v51, v56, v57
	v_cvt_pk_bf16_f32 v52, v52, v53
	v_cvt_pk_bf16_f32 v53, v58, v59
	global_store_dwordx4 v[70:71], v[50:53], off
	global_load_dwordx4 v[50:53], v[72:73], off
	v_lshl_add_u64 v[56:57], s[14:15], 0, v[54:55]
	v_lshl_add_u64 v[54:55], s[6:7], 0, v[54:55]
	s_waitcnt vmcnt(0)
	v_lshlrev_b32_e32 v58, 16, v50
	v_and_b32_e32 v59, 0xffff0000, v50
	v_lshlrev_b32_e32 v50, 16, v51
	v_and_b32_e32 v51, 0xffff0000, v51
	v_lshlrev_b32_e32 v60, 16, v52
	v_and_b32_e32 v61, 0xffff0000, v52
	v_lshlrev_b32_e32 v52, 16, v53
	v_and_b32_e32 v53, 0xffff0000, v53
	v_pk_mul_f32 v[48:49], v[48:49], v[50:51]
	v_pk_mul_f32 v[46:47], v[46:47], v[58:59]
	v_pk_mul_f32 v[50:51], v[44:45], v[52:53]
	v_pk_mul_f32 v[44:45], v[42:43], v[60:61]
	v_cvt_pk_bf16_f32 v42, v46, v47
	v_cvt_pk_bf16_f32 v43, v48, v49
	v_lshl_add_u64 v[52:53], s[6:7], 0, v[66:67]
	v_cvt_pk_bf16_f32 v44, v44, v45
	v_cvt_pk_bf16_f32 v45, v50, v51
	global_load_dwordx4 v[46:49], v[56:57], off
	v_lshl_add_u64 v[50:51], v[146:147], 0, s[36:37]
	global_store_dwordx4 v[52:53], v[42:45], off
	v_lshl_add_u64 v[56:57], s[14:15], 0, v[50:51]
	s_waitcnt vmcnt(1)
	v_lshlrev_b32_e32 v42, 16, v46
	v_and_b32_e32 v43, 0xffff0000, v46
	v_lshlrev_b32_e32 v44, 16, v47
	v_and_b32_e32 v45, 0xffff0000, v47
	v_lshlrev_b32_e32 v46, 16, v48
	v_and_b32_e32 v47, 0xffff0000, v48
	v_lshlrev_b32_e32 v48, 16, v49
	v_and_b32_e32 v49, 0xffff0000, v49
	v_pk_mul_f32 v[38:39], v[38:39], v[42:43]
	v_pk_mul_f32 v[42:43], v[36:37], v[48:49]
	v_pk_mul_f32 v[36:37], v[34:35], v[46:47]
	v_pk_mul_f32 v[40:41], v[40:41], v[44:45]
	v_cvt_pk_bf16_f32 v34, v38, v39
	v_lshl_add_u64 v[38:39], v[146:147], 0, s[40:41]
	v_cvt_pk_bf16_f32 v35, v40, v41
	v_cvt_pk_bf16_f32 v36, v36, v37
	v_cvt_pk_bf16_f32 v37, v42, v43
	global_store_dwordx4 v[54:55], v[34:37], off
	global_load_dwordx4 v[34:37], v[56:57], off
	v_lshl_add_u64 v[40:41], s[14:15], 0, v[38:39]
	v_lshl_add_u64 v[38:39], s[6:7], 0, v[38:39]
	s_waitcnt vmcnt(0)
	v_lshlrev_b32_e32 v42, 16, v34
	v_and_b32_e32 v43, 0xffff0000, v34
	v_lshlrev_b32_e32 v34, 16, v35
	v_and_b32_e32 v35, 0xffff0000, v35
	v_lshlrev_b32_e32 v44, 16, v36
	v_and_b32_e32 v45, 0xffff0000, v36
	v_lshlrev_b32_e32 v36, 16, v37
	v_and_b32_e32 v37, 0xffff0000, v37
	v_pk_mul_f32 v[32:33], v[32:33], v[34:35]
	v_pk_mul_f32 v[30:31], v[30:31], v[42:43]
	v_pk_mul_f32 v[34:35], v[28:29], v[36:37]
	v_pk_mul_f32 v[28:29], v[26:27], v[44:45]
	v_cvt_pk_bf16_f32 v26, v30, v31
	v_cvt_pk_bf16_f32 v27, v32, v33
	v_lshl_add_u64 v[36:37], s[6:7], 0, v[50:51]
	v_cvt_pk_bf16_f32 v28, v28, v29
	v_cvt_pk_bf16_f32 v29, v34, v35
	global_load_dwordx4 v[30:33], v[40:41], off
	v_lshl_add_u64 v[34:35], v[146:147], 0, s[44:45]
	global_store_dwordx4 v[36:37], v[26:29], off
	v_lshl_add_u64 v[40:41], s[14:15], 0, v[34:35]
	s_waitcnt vmcnt(1)
	v_lshlrev_b32_e32 v26, 16, v30
	v_and_b32_e32 v27, 0xffff0000, v30
	v_lshlrev_b32_e32 v28, 16, v31
	v_and_b32_e32 v29, 0xffff0000, v31
	v_lshlrev_b32_e32 v30, 16, v32
	v_and_b32_e32 v31, 0xffff0000, v32
	v_lshlrev_b32_e32 v32, 16, v33
	v_and_b32_e32 v33, 0xffff0000, v33
	v_pk_mul_f32 v[22:23], v[22:23], v[26:27]
	v_pk_mul_f32 v[26:27], v[20:21], v[32:33]
	v_pk_mul_f32 v[20:21], v[18:19], v[30:31]
	v_pk_mul_f32 v[24:25], v[24:25], v[28:29]
	v_cvt_pk_bf16_f32 v18, v22, v23
	v_lshl_add_u64 v[22:23], v[146:147], 0, s[54:55]
	v_cvt_pk_bf16_f32 v19, v24, v25
	v_cvt_pk_bf16_f32 v20, v20, v21
	v_cvt_pk_bf16_f32 v21, v26, v27
	global_store_dwordx4 v[38:39], v[18:21], off
	global_load_dwordx4 v[18:21], v[40:41], off
	v_lshl_add_u64 v[24:25], s[14:15], 0, v[22:23]
	s_waitcnt vmcnt(0)
	v_lshlrev_b32_e32 v26, 16, v18
	v_and_b32_e32 v27, 0xffff0000, v18
	v_lshlrev_b32_e32 v18, 16, v19
	v_and_b32_e32 v19, 0xffff0000, v19
	v_lshlrev_b32_e32 v28, 16, v20
	v_and_b32_e32 v29, 0xffff0000, v20
	v_lshlrev_b32_e32 v20, 16, v21
	v_and_b32_e32 v21, 0xffff0000, v21
	v_pk_mul_f32 v[16:17], v[16:17], v[18:19]
	v_pk_mul_f32 v[14:15], v[14:15], v[26:27]
	v_pk_mul_f32 v[18:19], v[12:13], v[20:21]
	v_pk_mul_f32 v[12:13], v[10:11], v[28:29]
	v_cvt_pk_bf16_f32 v10, v14, v15
	v_cvt_pk_bf16_f32 v11, v16, v17
	v_lshl_add_u64 v[20:21], s[6:7], 0, v[22:23]
	v_cvt_pk_bf16_f32 v12, v12, v13
	v_cvt_pk_bf16_f32 v13, v18, v19
	global_load_dwordx4 v[14:17], v[24:25], off
	v_lshl_add_u64 v[18:19], s[6:7], 0, v[34:35]
	global_store_dwordx4 v[18:19], v[10:13], off
	s_waitcnt vmcnt(1)
	s_nop 0
	v_lshlrev_b32_e32 v10, 16, v14
	v_and_b32_e32 v11, 0xffff0000, v14
	v_lshlrev_b32_e32 v12, 16, v15
	v_and_b32_e32 v13, 0xffff0000, v15
	v_lshlrev_b32_e32 v14, 16, v16
	v_and_b32_e32 v15, 0xffff0000, v16
	v_lshlrev_b32_e32 v16, 16, v17
	v_and_b32_e32 v17, 0xffff0000, v17
	v_pk_mul_f32 v[6:7], v[6:7], v[10:11]
	v_pk_mul_f32 v[10:11], v[4:5], v[16:17]
	v_pk_mul_f32 v[4:5], v[2:3], v[14:15]
	v_pk_mul_f32 v[8:9], v[8:9], v[12:13]
	v_cvt_pk_bf16_f32 v2, v6, v7
	s_nop 0
	v_cvt_pk_bf16_f32 v3, v8, v9
	v_cvt_pk_bf16_f32 v4, v4, v5
	v_cvt_pk_bf16_f32 v5, v10, v11
	global_store_dwordx4 v[20:21], v[2:5], off
	s_cbranch_vccnz .Lmy_pf4a_skip
	v_lshrrev_b32_e32 v252, 2, v1
	v_and_b32_e32 v253, 3, v1
	v_lshl_add_u32 v252, s58, 8, v252
	v_lshlrev_b32_e32 v252, 11, v252
	v_lshlrev_b32_e32 v253, 7, v253
	s_lshl_b32 s98, s56, 9
	v_add3_u32 v252, v252, v253, s98
	v_mov_b32_e32 v253, 0
	s_add_u32 s98, s14, 0x40000
	s_addc_u32 s99, s15, 0
	v_lshl_add_u64 v[250:251], s[14:15], 0, v[252:253]
	v_lshl_add_u64 v[252:253], s[98:99], 0, v[252:253]
	global_load_dword v255, v[250:251], off
	global_load_dword v255, v[252:253], off
.Lmy_pf4a_skip:
	s_cbranch_vccnz .LBB0_736
	s_andn2_b64 vcc, exec, s[12:13]
	s_cbranch_vccnz .LBB0_735
	s_barrier
	s_branch .LBB0_735
